# X1: grid barrier - dead XGEN(x) bump removed (nobody reads it since everyone polls TOPGEN) and the leader wave no longer waits for its fire-and-forget atomics before the exit barrier; on top of N3
# speedup vs baseline: 1.0089x; 1.0089x over previous
.LBB0_22:
	s_or_b64 exec, exec, s[0:1]
	v_readlane_b32 s0, v255, 7
	s_nop 3
	s_cmp_eq_u32 s0, 0
	s_cbranch_scc1 .Lgb_w0
	s_waitcnt vmcnt(0)
.Lgb_w0:
	s_waitcnt lgkmcnt(0)
	s_barrier
	s_mov_b64 s[0:1], 0

.LBB0_626:
	s_or_b64 exec, exec, s[4:5]
	s_mov_b64 s[4:5], exec
	v_mbcnt_lo_u32_b32 v0, s4, 0
	v_mbcnt_hi_u32_b32 v0, s5, v0
	v_cmp_eq_u32_e32 vcc, 0, v0
	s_nop 1
	s_and_saveexec_b64 s[6:7], vcc
	s_branch .LBB0_21
